# mix_post_b rows beside the GLU GEMM: OH1 and the seven HGRN2/GLA operand loads issued together with the OH load (2 round trips per row instead of 5)
# baseline (speedup 1.0000x reference)
.LBB0_1607:
	v_add_co_u32_e32 v0, vcc, 0x2d772000, v4
	s_nop 1
	v_addc_co_u32_e32 v1, vcc, 0, v5, vcc
	v_mov_b64_e32 v[0:1], v[120:121]
	v_mov_b64_e32 v[2:3], v[122:123]
	s_waitcnt vmcnt(0)
	v_lshlrev_b32_e32 v6, 16, v0
	v_and_b32_e32 v7, 0xffff0000, v0
	v_lshlrev_b32_e32 v0, 16, v1
	v_and_b32_e32 v1, 0xffff0000, v1
	v_pk_add_f32 v[34:35], v[34:35], v[0:1]
	v_lshlrev_b32_e32 v0, 16, v2
	v_and_b32_e32 v1, 0xffff0000, v2
	v_pk_add_f32 v[36:37], v[40:41], v[6:7]
	v_pk_add_f32 v[48:49], v[48:49], v[0:1]
	v_lshlrev_b32_e32 v0, 16, v3
	v_and_b32_e32 v1, 0xffff0000, v3
	v_pk_add_f32 v[32:33], v[32:33], v[0:1]
	v_mov_b32_e32 v41, v37
.LBB0_1608:
	v_add_co_u32_e32 v0, vcc, 0x2c652000, v4
	v_mov_b64_e32 v[8:9], v[124:125]
	v_mov_b64_e32 v[10:11], v[126:127]
	v_mov_b64_e32 v[12:13], v[128:129]
	v_mov_b64_e32 v[14:15], v[130:131]
	v_addc_co_u32_e32 v1, vcc, 0, v5, vcc
	v_mov_b64_e32 v[20:21], v[132:133]
	v_mov_b64_e32 v[22:23], v[134:135]
	v_lshl_add_u64 v[0:1], s[2:3], 0, v[96:97]
	v_add_co_u32_e32 v2, vcc, 0x1ec01000, v0
	v_pk_mul_f32 v[38:39], v[32:33], v[32:33]
	s_nop 0
	v_addc_co_u32_e32 v3, vcc, 0, v1, vcc
	v_add_co_u32_e32 v0, vcc, 0x1ec02000, v0
	v_mov_b64_e32 v[54:55], v[136:137]
	v_mov_b64_e32 v[56:57], v[138:139]
	s_nop 0
	v_addc_co_u32_e32 v1, vcc, 0, v1, vcc
	v_mov_b64_e32 v[16:17], v[140:141]
	v_mov_b64_e32 v[18:19], v[142:143]
	s_nop 0
	v_mov_b64_e32 v[0:1], v[144:145]
	v_mov_b64_e32 v[2:3], v[146:147]
	v_mov_b64_e32 v[4:5], v[148:149]
	v_mov_b64_e32 v[6:7], v[150:151]
	v_pk_mul_f32 v[44:45], v[48:49], v[48:49]
	v_pk_mul_f32 v[46:47], v[34:35], v[34:35]
	v_mov_b32_e32 v37, v34
	v_mov_b32_e32 v34, v41
	v_mov_b32_e32 v42, v48
	v_mov_b32_e32 v43, v32
	v_mov_b32_e32 v32, v49
	v_mov_b32_e32 v49, v36
	s_brev_b32 s0, 60
	s_add_i32 s6, s6, s4
	s_add_u32 s8, s8, s10
	s_addc_u32 s9, s9, s11
	s_add_u32 s12, s12, s14
	s_addc_u32 s13, s13, s15
	s_waitcnt vmcnt(0)
	v_mov_b32_e32 v60, v8
	v_mov_b32_e32 v59, v14
	v_mov_b32_e32 v14, v13
	v_mov_b32_e32 v61, v10
	v_mov_b32_e32 v10, v9
	v_lshlrev_b32_e32 v13, 16, v21
	v_and_b32_e32 v9, 0xffff0000, v21
	v_and_b32_e32 v8, 0xffff0000, v20
	v_mov_b32_e32 v58, v12
	v_lshlrev_b32_e32 v12, 16, v20
	v_mov_b32_e32 v66, v9
	v_mov_b32_e32 v67, v13
	v_mov_b32_e32 v40, v8
	v_mov_b32_e32 v48, v12
	v_pk_mul_f32 v[66:67], v[66:67], v[66:67]
	v_pk_mul_f32 v[40:41], v[40:41], v[40:41]
	v_lshlrev_b32_e32 v20, 16, v16
	v_lshlrev_b32_e32 v63, 16, v55
	v_lshlrev_b32_e32 v62, 16, v54
	v_and_b32_e32 v54, 0xffff0000, v54
	v_and_b32_e32 v16, 0xffff0000, v16
	v_pk_fma_f32 v[40:41], v[48:49], v[48:49], v[40:41]
	v_pk_mov_b32 v[48:49], v[66:67], v[46:47] op_sel:[1,0]
	v_mul_f32_e32 v46, 0xbfb8aa3b, v20
	v_mul_f32_e32 v69, 0xbfb8aa3b, v54
	v_mul_f32_e32 v70, 0xbfb8aa3b, v63
	v_exp_f32_e32 v46, v46
	v_mul_f32_e32 v67, 0xbfb8aa3b, v16
	v_exp_f32_e32 v69, v69
	v_exp_f32_e32 v70, v70
	v_exp_f32_e32 v67, v67
	v_lshlrev_b32_e32 v21, 16, v17
	v_lshlrev_b32_e32 v65, 16, v57
	v_lshlrev_b32_e32 v64, 16, v56
	v_and_b32_e32 v56, 0xffff0000, v56
	v_and_b32_e32 v17, 0xffff0000, v17
	v_add_f32_e32 v46, 1.0, v46
	v_mov_b32_e32 v78, v4
	v_mul_f32_e32 v4, 0xbfb8aa3b, v21
	v_mul_f32_e32 v73, 0xbfb8aa3b, v56
	v_mul_f32_e32 v74, 0xbfb8aa3b, v65
	v_add_f32_e32 v69, 1.0, v69
	v_add_f32_e32 v76, 1.0, v70
	v_pk_add_f32 v[40:41], v[48:49], v[40:41]
	v_rcp_f32_e32 v48, v46
	v_add_f32_e32 v46, 1.0, v67
	v_exp_f32_e32 v4, v4
	v_mov_b32_e32 v79, v6
	v_mul_f32_e32 v6, 0xbfb8aa3b, v17
	v_exp_f32_e32 v73, v73
	v_exp_f32_e32 v74, v74
	v_rcp_f32_e32 v70, v69
	v_rcp_f32_e32 v69, v76
	v_rcp_f32_e32 v76, v46
	v_exp_f32_e32 v46, v6
	v_add_f32_e32 v4, 1.0, v4
	v_add_f32_e32 v73, 1.0, v73
	v_add_f32_e32 v77, 1.0, v74
	v_rcp_f32_e32 v49, v4
	v_add_f32_e32 v4, 1.0, v46
	v_rcp_f32_e32 v74, v73
	v_rcp_f32_e32 v73, v77
	v_rcp_f32_e32 v77, v4
	v_lshlrev_b32_e32 v4, 16, v22
	v_and_b32_e32 v22, 0xffff0000, v22
	v_mov_b32_e32 v82, v22
	v_mov_b32_e32 v83, v4
	v_mov_b32_e32 v6, v5
	v_lshlrev_b32_e32 v5, 16, v23
	v_and_b32_e32 v23, 0xffff0000, v23
	v_pk_mul_f32 v[82:83], v[82:83], v[82:83]
	v_mov_b32_e32 v67, v47
	v_mov_b32_e32 v84, v23
	v_mov_b32_e32 v85, v5
	v_pk_add_f32 v[40:41], v[66:67], v[40:41]
	v_pk_mov_b32 v[46:47], v[82:83], v[44:45] op_sel:[1,0]
	v_pk_mul_f32 v[84:85], v[84:85], v[84:85]
	v_pk_add_f32 v[40:41], v[46:47], v[40:41]
	v_mov_b32_e32 v83, v45
	v_pk_add_f32 v[40:41], v[82:83], v[40:41]
	v_pk_mov_b32 v[44:45], v[84:85], v[38:39] op_sel:[1,0]
	v_mov_b32_e32 v85, v39
	v_pk_add_f32 v[40:41], v[44:45], v[40:41]
	v_lshlrev_b32_e32 v80, 16, v18
	v_pk_add_f32 v[38:39], v[84:85], v[40:41]
	ds_bpermute_b32 v41, v50, v39
	ds_bpermute_b32 v40, v50, v38
	v_and_b32_e32 v18, 0xffff0000, v18
	v_lshlrev_b32_e32 v81, 16, v19
	v_mul_f32_e32 v45, 0xbfb8aa3b, v18
	v_exp_f32_e32 v45, v45
	s_waitcnt lgkmcnt(0)
	v_pk_add_f32 v[38:39], v[38:39], v[40:41]
	ds_bpermute_b32 v41, v51, v39
	ds_bpermute_b32 v40, v51, v38
	v_mul_f32_e32 v46, 0xbfb8aa3b, v81
	v_exp_f32_e32 v47, v46
	v_and_b32_e32 v19, 0xffff0000, v19
	v_add_f32_e32 v45, 1.0, v45
	s_waitcnt lgkmcnt(0)
	v_pk_add_f32 v[38:39], v[38:39], v[40:41]
	ds_bpermute_b32 v41, v52, v39
	ds_bpermute_b32 v40, v52, v38
	v_and_b32_e32 v55, 0xffff0000, v55
	v_rcp_f32_e32 v46, v45
	v_add_f32_e32 v45, 1.0, v47
	v_mul_f32_e32 v47, 0xbfb8aa3b, v19
	s_waitcnt lgkmcnt(0)
	v_pk_add_f32 v[38:39], v[38:39], v[40:41]
	ds_bpermute_b32 v41, v53, v39
	ds_bpermute_b32 v40, v53, v38
	v_mul_f32_e32 v71, 0xbfb8aa3b, v55
	v_exp_f32_e32 v47, v47
	v_and_b32_e32 v57, 0xffff0000, v57
	v_mul_f32_e32 v72, 0xbfb8aa3b, v64
	s_waitcnt lgkmcnt(0)
	v_pk_add_f32 v[38:39], v[38:39], v[40:41]
	v_exp_f32_e32 v71, v71
	v_pk_fma_f32 v[38:39], v[38:39], s[0:1], v[242:243] op_sel_hi:[1,0,0]
	v_mul_f32_e32 v75, 0xbfb8aa3b, v57
	v_mul_f32_e32 v40, 0x4b800000, v39
	v_cmp_gt_f32_e32 vcc, s45, v39
	v_exp_f32_e32 v72, v72
	v_mul_f32_e32 v68, 0xbfb8aa3b, v62
	v_cndmask_b32_e32 v39, v39, v40, vcc
	v_rsq_f32_e32 v39, v39
	v_exp_f32_e32 v75, v75
	v_exp_f32_e32 v68, v68
	v_add_f32_e32 v40, 1.0, v47
	v_add_f32_e32 v71, 1.0, v71
	v_rcp_f32_e32 v47, v40
	v_mul_f32_e32 v40, 0x45800000, v39
	v_add_f32_e32 v72, 1.0, v72
	v_rcp_f32_e32 v71, v71
	v_cndmask_b32_e32 v40, v39, v40, vcc
	v_add_f32_e32 v75, 1.0, v75
	v_rcp_f32_e32 v72, v72
	v_pk_mul_f32 v[34:35], v[34:35], v[40:41] op_sel_hi:[1,0]
	v_add_f32_e32 v68, 1.0, v68
	v_rcp_f32_e32 v75, v75
	v_pk_mul_f32 v[14:15], v[14:15], v[34:35]
	v_pk_mul_f32 v[34:35], v[42:43], v[40:41] op_sel_hi:[1,0]
	v_rcp_f32_e32 v68, v68
	v_pk_mul_f32 v[14:15], v[14:15], v[54:55]
	v_pk_mul_f32 v[34:35], v[60:61], v[34:35]
	v_pk_mul_f32 v[32:33], v[32:33], v[40:41] op_sel_hi:[1,0]
	v_pk_mul_f32 v[36:37], v[36:37], v[40:41] op_sel_hi:[1,0]
	v_pk_mul_f32 v[14:15], v[70:71], v[14:15]
	v_pk_mul_f32 v[34:35], v[34:35], v[64:65]
	v_pk_mul_f32 v[10:11], v[10:11], v[32:33]
	v_pk_mul_f32 v[36:37], v[58:59], v[36:37]
	v_pk_mul_f32 v[34:35], v[72:73], v[34:35]
	v_pk_mul_f32 v[10:11], v[10:11], v[56:57]
	v_bfe_u32 v39, v15, 16, 1
	v_pk_mul_f32 v[36:37], v[36:37], v[62:63]
	v_pk_mul_f32 v[10:11], v[74:75], v[10:11]
	v_add3_u32 v15, v15, v39, s48
	v_bfe_u32 v39, v34, 16, 1
	v_pk_mul_f32 v[36:37], v[68:69], v[36:37]
	v_bfe_u32 v32, v11, 16, 1
	v_bfe_u32 v33, v10, 16, 1
	v_add3_u32 v34, v34, v39, s48
	v_add3_u32 v10, v10, v33, s48
	v_add3_u32 v11, v11, v32, s48
	v_bfe_u32 v32, v36, 16, 1
	v_lshrrev_b32_e32 v34, 16, v34
	v_bfe_u32 v40, v14, 16, 1
	v_add3_u32 v32, v36, v32, s48
	v_and_or_b32 v34, v10, s36, v34
	v_mul_f32_e32 v10, 0x4b800000, v38
	v_cmp_gt_f32_e32 vcc, s45, v38
	v_add3_u32 v14, v14, v40, s48
	v_lshrrev_b32_e32 v32, 16, v32
	v_cndmask_b32_e32 v10, v38, v10, vcc
	v_and_or_b32 v32, v14, s36, v32
	v_rsq_f32_e32 v14, v10
	v_bfe_u32 v33, v37, 16, 1
	v_mul_f32_e32 v44, 0xbfb8aa3b, v80
	v_add3_u32 v33, v37, v33, s48
	v_exp_f32_e32 v44, v44
	v_lshrrev_b32_e32 v33, 16, v33
	v_and_or_b32 v33, v15, s36, v33
	v_mul_f32_e32 v15, 0x45800000, v14
	v_cndmask_b32_e32 v14, v14, v15, vcc
	v_pk_mul_f32 v[8:9], v[14:15], v[8:9] op_sel_hi:[0,1]
	v_add_f32_e32 v44, 1.0, v44
	v_pk_mul_f32 v[6:7], v[6:7], v[8:9]
	v_pk_mul_f32 v[4:5], v[14:15], v[4:5] op_sel_hi:[0,1]
	v_mov_b32_e32 v8, v0
	v_mov_b32_e32 v9, v2
	v_rcp_f32_e32 v44, v44
	v_rcp_f32_e32 v45, v45
	v_pk_mul_f32 v[4:5], v[8:9], v[4:5]
	v_pk_mul_f32 v[8:9], v[14:15], v[22:23] op_sel_hi:[0,1]
	v_mov_b32_e32 v2, v1
	v_bfe_u32 v40, v35, 16, 1
	v_pk_mul_f32 v[12:13], v[14:15], v[12:13] op_sel_hi:[0,1]
	v_pk_mul_f32 v[0:1], v[2:3], v[8:9]
	v_add3_u32 v35, v35, v40, s48
	v_pk_mul_f32 v[12:13], v[78:79], v[12:13]
	v_pk_mul_f32 v[6:7], v[6:7], v[16:17]
	v_pk_mul_f32 v[0:1], v[0:1], v[18:19]
	v_lshrrev_b32_e32 v35, 16, v35
	v_add_co_u32_e64 v10, s[0:1], s7, v30
	v_pk_mul_f32 v[12:13], v[12:13], v[20:21]
	v_pk_mul_f32 v[6:7], v[76:77], v[6:7]
	v_pk_mul_f32 v[4:5], v[4:5], v[80:81]
	v_pk_mul_f32 v[0:1], v[46:47], v[0:1]
	v_and_or_b32 v35, v11, s36, v35
	v_addc_co_u32_e64 v11, s[0:1], 0, v31, s[0:1]
	v_pk_mul_f32 v[12:13], v[48:49], v[12:13]
	v_pk_mul_f32 v[4:5], v[44:45], v[4:5]
	v_bfe_u32 v2, v1, 16, 1
	v_bfe_u32 v3, v0, 16, 1
	v_bfe_u32 v8, v7, 16, 1
	v_bfe_u32 v9, v6, 16, 1
	v_add3_u32 v6, v6, v9, s48
	v_add3_u32 v7, v7, v8, s48
	v_add3_u32 v0, v0, v3, s48
	v_add3_u32 v1, v1, v2, s48
	v_bfe_u32 v2, v12, 16, 1
	v_bfe_u32 v3, v13, 16, 1
	v_bfe_u32 v8, v4, 16, 1
	v_bfe_u32 v9, v5, 16, 1
	s_mul_i32 s0, s4, 0x3000
	v_add3_u32 v5, v5, v9, s48
	v_add3_u32 v4, v4, v8, s48
	v_add3_u32 v3, v13, v3, s48
	v_add3_u32 v2, v12, v2, s48
	s_add_u32 s2, s2, s0
	s_mul_hi_i32 s0, s4, 0x3000
	v_lshrrev_b32_e32 v8, 16, v2
	v_lshrrev_b32_e32 v9, 16, v3
	v_lshrrev_b32_e32 v2, 16, v4
	v_lshrrev_b32_e32 v3, 16, v5
	s_addc_u32 s3, s3, s0
	v_and_or_b32 v3, v1, s36, v3
	v_and_or_b32 v2, v0, s36, v2
	v_and_or_b32 v1, v7, s36, v9
	v_and_or_b32 v0, v6, s36, v8
	s_cmpk_lt_i32 s6, 0x2240
	global_store_dwordx4 v[10:11], v[32:35], off offset:2048
	global_store_dwordx4 v[10:11], v[0:3], off offset:3072
	s_cbranch_scc0 .LBB0_1613

.LBB0_1611:
	s_nop 1
	v_add_co_u32_e32 v0, vcc, 0x2b532000, v4
	s_nop 1
	v_addc_co_u32_e32 v1, vcc, 0, v5, vcc
	global_load_dwordx4 v[0:3], v[0:1], off
	s_mov_b64 s[98:99], 0x2d772000
	v_lshl_add_u64 v[152:153], v[4:5], 0, s[98:99]
	global_load_dwordx4 v[120:123], v[152:153], off
	global_load_dwordx4 v[124:127], v[24:25], off offset:16
	global_load_dwordx4 v[128:131], v[24:25], off
	s_mov_b64 s[98:99], 0x2c652000
	v_lshl_add_u64 v[152:153], v[4:5], 0, s[98:99]
	global_load_dwordx4 v[132:135], v[152:153], off
	v_lshl_add_u64 v[154:155], s[2:3], 0, v[96:97]
	s_mov_b64 s[98:99], 0x1ec01000
	v_lshl_add_u64 v[152:153], v[154:155], 0, s[98:99]
	global_load_dwordx4 v[136:139], v[152:153], off offset:3584
	s_mov_b64 s[98:99], 0x1ec02000
	v_lshl_add_u64 v[152:153], v[154:155], 0, s[98:99]
	global_load_dwordx4 v[140:143], v[152:153], off offset:2592
	global_load_dwordx4 v[144:147], v[26:27], off offset:16
	global_load_dwordx4 v[148:151], v[26:27], off
	s_andn2_b64 vcc, exec, s[0:1]
	s_waitcnt vmcnt(0)
	v_lshlrev_b32_e32 v40, 16, v0
	v_and_b32_e32 v41, 0xffff0000, v0
	v_lshlrev_b32_e32 v34, 16, v1
	v_and_b32_e32 v35, 0xffff0000, v1
	v_lshlrev_b32_e32 v48, 16, v2
	v_and_b32_e32 v49, 0xffff0000, v2
	v_lshlrev_b32_e32 v32, 16, v3
	v_and_b32_e32 v33, 0xffff0000, v3
	s_cbranch_vccz .LBB0_1607
	v_mov_b32_e32 v36, v40
	s_branch .LBB0_1608
